# prompt attention streamed loop: K/V fragment ds_reads pipelined 4-5 deep instead of one wait per MFMA, V fragments prefetched under exp (16 extra VGPRs)
# speedup vs baseline: 1.0326x; 1.0326x over previous
.LBB0_1533:
	v_cvt_pk_bf16_f32 v10, v160, v161
	v_cvt_pk_bf16_f32 v11, v162, v163
	v_cvt_pk_bf16_f32 v12, v164, v165
	v_cvt_pk_bf16_f32 v13, v166, v167
	s_nop 4
	ds_read_b128 v[144:147], v8 offset:20480
	ds_read_b128 v[148:151], v8 offset:21504
	ds_read_b128 v[152:155], v8 offset:22528
	ds_read_b128 v[156:159], v8 offset:23552
	v_add_f32_e32 v1, v1, v9
	s_waitcnt lgkmcnt(4)
	v_mfma_f32_32x32x16_bf16 v[16:31], v[10:13], v[240:243], v[16:31]
	v_mfma_f32_32x32x16_bf16 v[32:47], v[10:13], v[244:247], v[32:47]
	v_mfma_f32_32x32x16_bf16 v[96:111], v[10:13], v[248:251], v[96:111]
	v_mfma_f32_32x32x16_bf16 v[80:95], v[10:13], v[252:255], v[80:95]
	v_cvt_pk_bf16_f32 v10, v168, v169
	v_cvt_pk_bf16_f32 v11, v170, v171
	v_cvt_pk_bf16_f32 v12, v172, v173
	v_cvt_pk_bf16_f32 v13, v174, v175
	s_waitcnt lgkmcnt(3)
	s_nop 0
	v_mfma_f32_32x32x16_bf16 v[16:31], v[10:13], v[144:147], v[16:31]
	s_waitcnt lgkmcnt(2)
	v_mfma_f32_32x32x16_bf16 v[32:47], v[10:13], v[148:151], v[32:47]
	s_waitcnt lgkmcnt(1)
	v_mfma_f32_32x32x16_bf16 v[96:111], v[10:13], v[152:155], v[96:111]
	s_waitcnt lgkmcnt(0)
	v_mfma_f32_32x32x16_bf16 v[80:95], v[10:13], v[156:159], v[80:95]

.LBB0_1547:
	s_lshl_b64 s[4:5], 1, s40
	s_waitcnt lgkmcnt(0)
	v_and_b32_e32 v9, s5, v215
	v_and_b32_e32 v8, s4, v214
	v_cmp_ne_u64_e32 vcc, 0, v[8:9]
	s_add_i32 s40, s59, s68
	s_or_b64 s[4:5], s[6:7], vcc
	s_sub_i32 s36, s40, 63
	s_cmpk_gt_i32 s36, 0x1ff
	s_cselect_b64 vcc, -1, 0
	v_cndmask_b32_e64 v8, 0, 1, s[4:5]
	s_and_b64 s[46:47], s[6:7], vcc
	v_cmp_ne_u32_e32 vcc, 0, v8
	s_cmp_eq_u64 vcc, 0
	s_cselect_b64 vcc, -1, 0
	s_or_b64 s[46:47], vcc, s[46:47]
	s_and_b64 vcc, exec, s[46:47]
	s_cbranch_vccnz .LBB0_1534
	s_add_i32 s46, s40, 7
	s_and_b32 s40, s76, 0x18000
	v_add_u32_e32 v8, s40, v232
	ds_read_b128 v[10:13], v8
	ds_read_b128 v[160:163], v8 offset:1024
	ds_read_b128 v[164:167], v8 offset:2048
	ds_read_b128 v[168:171], v8 offset:3072
	ds_read_b128 v[172:175], v8 offset:4096
	s_cmpk_gt_i32 s36, 0x7f
	s_cselect_b64 s[40:41], -1, 0
	s_cmp_lt_i32 s46, s9
	s_cselect_b64 s[46:47], -1, 0
	s_and_b64 s[40:41], s[40:41], s[46:47]
	s_andn2_b64 vcc, exec, s[40:41]
	s_mov_b64 s[40:41], -1
	s_waitcnt lgkmcnt(4)
	v_mfma_f32_32x32x16_bf16 v[144:159], v[10:13], v[176:179], 0
	ds_read_b128 v[10:13], v8 offset:5120
	s_waitcnt lgkmcnt(4)
	v_mfma_f32_32x32x16_bf16 v[144:159], v[160:163], v[180:183], v[144:159]
	ds_read_b128 v[160:163], v8 offset:6144
	s_waitcnt lgkmcnt(4)
	v_mfma_f32_32x32x16_bf16 v[144:159], v[164:167], v[184:187], v[144:159]
	ds_read_b128 v[164:167], v8 offset:7168
	s_waitcnt lgkmcnt(4)
	v_mfma_f32_32x32x16_bf16 v[144:159], v[168:171], v[188:191], v[144:159]
	ds_read_b128 v[240:243], v8 offset:16384
	ds_read_b128 v[244:247], v8 offset:17408
	ds_read_b128 v[248:251], v8 offset:18432
	ds_read_b128 v[252:255], v8 offset:19456
	s_waitcnt lgkmcnt(7)
	v_mfma_f32_32x32x16_bf16 v[144:159], v[172:175], v[192:195], v[144:159]
	s_waitcnt lgkmcnt(6)
	v_mfma_f32_32x32x16_bf16 v[144:159], v[10:13], v[196:199], v[144:159]
	s_waitcnt lgkmcnt(5)
	v_mfma_f32_32x32x16_bf16 v[144:159], v[160:163], v[200:203], v[144:159]
	s_waitcnt lgkmcnt(4)
	v_mfma_f32_32x32x16_bf16 v[144:159], v[164:167], v[204:207], v[144:159]
	s_cbranch_vccz .LBB0_1582
	v_add_u32_e32 v11, s59, v6
	v_cmp_gt_u32_e32 vcc, s9, v11
	v_mov_b32_e32 v9, 0
	v_mov_b32_e32 v10, 0
	s_and_saveexec_b64 s[40:41], vcc
	s_cbranch_execz .LBB0_1551
	v_min_u32_e32 v10, 0x80, v11
	v_lshl_add_u32 v10, v10, 2, v226
	ds_read_b32 v10, v10
	s_waitcnt lgkmcnt(0)
	s_nop 0
	v_add_f32_e32 v10, v144, v10
	v_exp_f32_e32 v10, v10

	.amdhsa_kernel _Z6mk_fwd4Args
		.amdhsa_group_segment_fixed_size 0
		.amdhsa_private_segment_fixed_size 0
		.amdhsa_kernarg_size 536
		.amdhsa_user_sgpr_count 2
		.amdhsa_user_sgpr_dispatch_ptr 0
		.amdhsa_user_sgpr_queue_ptr 0
		.amdhsa_user_sgpr_kernarg_segment_ptr 1
		.amdhsa_user_sgpr_dispatch_id 0
		.amdhsa_user_sgpr_kernarg_preload_length 0
		.amdhsa_user_sgpr_kernarg_preload_offset 0
		.amdhsa_user_sgpr_private_segment_size 0
		.amdhsa_uses_dynamic_stack 0
		.amdhsa_enable_private_segment 0
		.amdhsa_system_sgpr_workgroup_id_x 1
		.amdhsa_system_sgpr_workgroup_id_y 0
		.amdhsa_system_sgpr_workgroup_id_z 0
		.amdhsa_system_sgpr_workgroup_info 0
		.amdhsa_system_vgpr_workitem_id 0
		.amdhsa_next_free_vgpr 256
		.amdhsa_next_free_sgpr 98
		.amdhsa_accum_offset 256
		.amdhsa_reserve_vcc 1
		.amdhsa_float_round_mode_32 0
		.amdhsa_float_round_mode_16_64 0
		.amdhsa_float_denorm_mode_32 3
		.amdhsa_float_denorm_mode_16_64 3
		.amdhsa_dx10_clamp 1
		.amdhsa_ieee_mode 1
		.amdhsa_fp16_overflow 0
		.amdhsa_tg_split 0
		.amdhsa_exception_fp_ieee_invalid_op 0
		.amdhsa_exception_fp_denorm_src 0
		.amdhsa_exception_fp_ieee_div_zero 0
		.amdhsa_exception_fp_ieee_overflow 0
		.amdhsa_exception_fp_ieee_underflow 0
		.amdhsa_exception_fp_ieee_inexact 0
		.amdhsa_exception_int_div_zero 0
	.end_amdhsa_kernel

amdhsa.kernels:
  - .agpr_count:     0
    .args:
      - .offset:         0
        .size:           280
        .value_kind:     by_value
      - .offset:         280
        .size:           4
        .value_kind:     hidden_block_count_x
      - .offset:         284
        .size:           4
        .value_kind:     hidden_block_count_y
      - .offset:         288
        .size:           4
        .value_kind:     hidden_block_count_z
      - .offset:         292
        .size:           2
        .value_kind:     hidden_group_size_x
      - .offset:         294
        .size:           2
        .value_kind:     hidden_group_size_y
      - .offset:         296
        .size:           2
        .value_kind:     hidden_group_size_z
      - .offset:         298
        .size:           2
        .value_kind:     hidden_remainder_x
      - .offset:         300
        .size:           2
        .value_kind:     hidden_remainder_y
      - .offset:         302
        .size:           2
        .value_kind:     hidden_remainder_z
      - .offset:         320
        .size:           8
        .value_kind:     hidden_global_offset_x
      - .offset:         328
        .size:           8
        .value_kind:     hidden_global_offset_y
      - .offset:         336
        .size:           8
        .value_kind:     hidden_global_offset_z
      - .offset:         344
        .size:           2
        .value_kind:     hidden_grid_dims
      - .offset:         400
        .size:           4
        .value_kind:     hidden_dynamic_lds_size
    .group_segment_fixed_size: 0
    .kernarg_segment_align: 8
    .kernarg_segment_size: 536
    .language:       OpenCL C
    .language_version:
      - 2
      - 0
    .max_flat_workgroup_size: 512
    .name:           _Z6mk_fwd4Args
    .private_segment_fixed_size: 0
    .sgpr_count:     104
    .sgpr_spill_count: 209
    .symbol:         _Z6mk_fwd4Args.kd
    .uniform_work_group_size: 1
    .uses_dynamic_stack: false
    .vgpr_count:     256
    .vgpr_spill_count: 0
    .wavefront_size: 64
